# attention loop: 3 counted lgkmcnt waits inside QK chain instead of 9; lrun add moved out of the PV MFMA chain
# baseline (speedup 1.0000x reference)
.LBB0_554:
	s_or_b64 exec, exec, s[6:7]
	global_load_dwordx4 v[2:5], v[174:175], off
	s_add_i32 s7, s64, 3
	s_and_b32 s6, s7, 1
	s_cmp_gt_i32 s7, s26
	s_cbranch_scc1 .LBB0_558
	s_mul_i32 s7, s6, 0x3400
	v_add_u32_e32 v0, s7, v169
	ds_read_b128 v[6:9], v0
	ds_read_b128 v[10:13], v0 offset:32
	ds_read_b128 v[128:131], v0 offset:6656
	ds_read_b128 v[132:135], v0 offset:6688
	ds_read_b128 v[136:139], v0 offset:64
	ds_read_b128 v[140:143], v0 offset:96
	ds_read_b128 v[144:147], v0 offset:6720
	ds_read_b128 v[148:151], v0 offset:6752
	ds_read_b128 v[180:183], v0 offset:128
	ds_read_b128 v[184:187], v0 offset:160
	ds_read_b128 v[188:191], v0 offset:6784
	ds_read_b128 v[192:195], v0 offset:6816
	s_waitcnt lgkmcnt(8)
	v_mfma_f32_32x32x16_bf16 v[80:95], v[6:9], v[116:119], v[48:63]
	v_mfma_f32_32x32x16_bf16 v[64:79], v[128:131], v[116:119], v[48:63]
	v_mfma_f32_32x32x16_bf16 v[80:95], v[10:13], v[112:115], v[80:95]
	v_mfma_f32_32x32x16_bf16 v[64:79], v[132:135], v[112:115], v[64:79]
	s_waitcnt lgkmcnt(4)
	v_mfma_f32_32x32x16_bf16 v[80:95], v[136:139], v[108:111], v[80:95]
	v_mfma_f32_32x32x16_bf16 v[64:79], v[144:147], v[108:111], v[64:79]
	v_mfma_f32_32x32x16_bf16 v[80:95], v[140:143], v[104:107], v[80:95]
	v_mfma_f32_32x32x16_bf16 v[64:79], v[148:151], v[104:107], v[64:79]
	s_waitcnt lgkmcnt(0)
	v_mfma_f32_32x32x16_bf16 v[80:95], v[180:183], v[120:123], v[80:95]
	v_mfma_f32_32x32x16_bf16 v[64:79], v[188:191], v[120:123], v[64:79]
	v_mfma_f32_32x32x16_bf16 v[80:95], v[184:187], v[124:127], v[80:95]
	v_mfma_f32_32x32x16_bf16 v[64:79], v[192:195], v[124:127], v[64:79]
	s_mul_i32 s7, s6, 0x2200
	v_add_u32_e32 v0, s7, v165
	v_add_u32_e32 v6, 0x6800, v0
	v_add_u32_e32 v0, 0x7800, v0
	ds_read2_b64 v[148:151], v6 offset1:2
	ds_read2_b64 v[144:147], v6 offset0:4 offset1:6
	ds_read2_b64 v[140:143], v6 offset0:8 offset1:10
	ds_read2_b64 v[136:139], v6 offset0:12 offset1:14
	ds_read2_b64 v[132:135], v0 offset0:32 offset1:34
	ds_read2_b64 v[128:131], v0 offset0:36 offset1:38
	ds_read2_b64 v[10:13], v0 offset0:40 offset1:42
	ds_read2_b64 v[6:9], v0 offset0:44 offset1:46
	v_max_f32_e32 v15, v65, v65
	v_max_f32_e32 v161, v64, v64
	v_max_f32_e32 v15, v161, v15
	v_max3_f32 v0, v80, v81, v82
	v_max3_f32 v15, v15, v66, v67
	v_max3_f32 v0, v0, v83, v84
	v_max3_f32 v15, v15, v68, v69
	v_max3_f32 v0, v0, v85, v86
	v_max3_f32 v15, v15, v70, v71
	v_max3_f32 v0, v0, v87, v88
	v_max3_f32 v15, v15, v72, v73
	v_max3_f32 v0, v0, v89, v90
	v_max3_f32 v15, v15, v74, v75
	v_max3_f32 v0, v0, v91, v92
	v_max3_f32 v15, v15, v76, v77
	v_max3_f32 v0, v0, v93, v94
	v_max3_f32 v15, v15, v78, v79
	v_max3_f32 v0, v0, v95, v15
	v_mov_b32_e32 v15, v0
	s_nop 1
	v_permlane32_swap_b32_e32 v0, v15
	v_max_f32_e32 v15, v15, v15
	v_max_f32_e32 v0, v0, v0
	v_max_f32_e32 v0, v0, v15
	v_cmp_lt_f32_e32 vcc, s56, v0
	s_cbranch_vccz .LBB0_557
	s_nop 0
	v_cndmask_b32_e32 v0, 0, v0, vcc
	v_exp_f32_e64 v180, -v0
	v_add_f32_e32 v158, v158, v0
	v_xor_b32_e32 v48, 0x80000000, v158
	v_mov_b32_e32 v49, v48
	v_mov_b32_e32 v50, v48
	v_mov_b32_e32 v51, v48
	v_mov_b32_e32 v52, v48
	v_mov_b32_e32 v53, v48
	v_mov_b32_e32 v54, v48
	v_mov_b32_e32 v55, v48
	v_mov_b32_e32 v56, v48
	v_mov_b32_e32 v57, v48
	v_mov_b32_e32 v58, v48
	v_mov_b32_e32 v59, v48
	v_mov_b32_e32 v60, v48
	v_mov_b32_e32 v61, v48
	v_mov_b32_e32 v62, v48
	v_mov_b32_e32 v63, v48
	v_pk_add_f32 v[80:81], v[80:81], v[0:1] op_sel_hi:[1,0] neg_lo:[0,1] neg_hi:[0,1]
	v_pk_add_f32 v[64:65], v[64:65], v[0:1] op_sel_hi:[1,0] neg_lo:[0,1] neg_hi:[0,1]
	v_pk_add_f32 v[82:83], v[82:83], v[0:1] op_sel_hi:[1,0] neg_lo:[0,1] neg_hi:[0,1]
	v_pk_add_f32 v[66:67], v[66:67], v[0:1] op_sel_hi:[1,0] neg_lo:[0,1] neg_hi:[0,1]
	v_pk_add_f32 v[84:85], v[84:85], v[0:1] op_sel_hi:[1,0] neg_lo:[0,1] neg_hi:[0,1]
	v_pk_add_f32 v[68:69], v[68:69], v[0:1] op_sel_hi:[1,0] neg_lo:[0,1] neg_hi:[0,1]
	v_pk_add_f32 v[86:87], v[86:87], v[0:1] op_sel_hi:[1,0] neg_lo:[0,1] neg_hi:[0,1]
	v_pk_add_f32 v[70:71], v[70:71], v[0:1] op_sel_hi:[1,0] neg_lo:[0,1] neg_hi:[0,1]
	v_pk_add_f32 v[88:89], v[88:89], v[0:1] op_sel_hi:[1,0] neg_lo:[0,1] neg_hi:[0,1]
	v_pk_add_f32 v[72:73], v[72:73], v[0:1] op_sel_hi:[1,0] neg_lo:[0,1] neg_hi:[0,1]
	v_pk_add_f32 v[90:91], v[90:91], v[0:1] op_sel_hi:[1,0] neg_lo:[0,1] neg_hi:[0,1]
	v_pk_add_f32 v[74:75], v[74:75], v[0:1] op_sel_hi:[1,0] neg_lo:[0,1] neg_hi:[0,1]
	v_pk_add_f32 v[92:93], v[92:93], v[0:1] op_sel_hi:[1,0] neg_lo:[0,1] neg_hi:[0,1]
	v_pk_add_f32 v[76:77], v[76:77], v[0:1] op_sel_hi:[1,0] neg_lo:[0,1] neg_hi:[0,1]
	v_pk_add_f32 v[94:95], v[94:95], v[0:1] op_sel_hi:[1,0] neg_lo:[0,1] neg_hi:[0,1]
	v_pk_add_f32 v[78:79], v[78:79], v[0:1] op_sel_hi:[1,0] neg_lo:[0,1] neg_hi:[0,1]
	v_pk_mul_f32 v[46:47], v[46:47], v[180:181] op_sel_hi:[1,0]
	v_pk_mul_f32 v[44:45], v[44:45], v[180:181] op_sel_hi:[1,0]
	v_pk_mul_f32 v[42:43], v[42:43], v[180:181] op_sel_hi:[1,0]
	v_pk_mul_f32 v[40:41], v[40:41], v[180:181] op_sel_hi:[1,0]
	v_pk_mul_f32 v[38:39], v[38:39], v[180:181] op_sel_hi:[1,0]
	v_pk_mul_f32 v[36:37], v[36:37], v[180:181] op_sel_hi:[1,0]
	v_pk_mul_f32 v[34:35], v[34:35], v[180:181] op_sel_hi:[1,0]
	v_pk_mul_f32 v[32:33], v[32:33], v[180:181] op_sel_hi:[1,0]
	v_pk_mul_f32 v[30:31], v[30:31], v[180:181] op_sel_hi:[1,0]
	v_pk_mul_f32 v[28:29], v[28:29], v[180:181] op_sel_hi:[1,0]
	v_pk_mul_f32 v[26:27], v[26:27], v[180:181] op_sel_hi:[1,0]
	v_pk_mul_f32 v[24:25], v[24:25], v[180:181] op_sel_hi:[1,0]
	v_pk_mul_f32 v[22:23], v[22:23], v[180:181] op_sel_hi:[1,0]
	v_pk_mul_f32 v[20:21], v[20:21], v[180:181] op_sel_hi:[1,0]
	v_pk_mul_f32 v[18:19], v[18:19], v[180:181] op_sel_hi:[1,0]
	v_pk_mul_f32 v[16:17], v[16:17], v[180:181] op_sel_hi:[1,0]
	v_mul_f32_e32 v159, v159, v180
.LBB0_557:
	v_exp_f32_e32 v196, v80
	v_exp_f32_e32 v212, v64
	v_exp_f32_e32 v197, v81
	v_exp_f32_e32 v213, v65
	v_exp_f32_e32 v198, v82
	v_exp_f32_e32 v214, v66
	v_add_f32_e32 v229, v212, v196
	v_exp_f32_e32 v199, v83
	v_exp_f32_e32 v215, v67
	v_add_f32_e32 v230, v213, v197
	v_add_f32_e32 v229, v230, v229
	v_exp_f32_e32 v200, v84
	v_exp_f32_e32 v216, v68
	v_add_f32_e32 v228, v214, v198
	v_add_f32_e32 v229, v228, v229
	v_exp_f32_e32 v201, v85
	v_exp_f32_e32 v217, v69
	v_add_f32_e32 v230, v215, v199
	v_add_f32_e32 v229, v230, v229
	v_exp_f32_e32 v202, v86
	v_exp_f32_e32 v218, v70
	v_add_f32_e32 v228, v216, v200
	v_add_f32_e32 v229, v228, v229
	v_exp_f32_e32 v203, v87
	v_exp_f32_e32 v219, v71
	v_add_f32_e32 v230, v217, v201
	v_add_f32_e32 v229, v230, v229
	v_exp_f32_e32 v204, v88
	v_exp_f32_e32 v220, v72
	v_add_f32_e32 v228, v218, v202
	v_add_f32_e32 v229, v228, v229
	v_exp_f32_e32 v205, v89
	v_exp_f32_e32 v221, v73
	v_add_f32_e32 v230, v219, v203
	v_add_f32_e32 v229, v230, v229
	v_exp_f32_e32 v206, v90
	v_exp_f32_e32 v222, v74
	v_add_f32_e32 v228, v220, v204
	v_add_f32_e32 v229, v228, v229
	v_exp_f32_e32 v207, v91
	v_exp_f32_e32 v223, v75
	v_add_f32_e32 v230, v221, v205
	v_add_f32_e32 v229, v230, v229
	v_exp_f32_e32 v208, v92
	v_exp_f32_e32 v224, v76
	v_add_f32_e32 v228, v222, v206
	v_add_f32_e32 v229, v228, v229
	v_exp_f32_e32 v209, v93
	v_exp_f32_e32 v225, v77
	v_add_f32_e32 v230, v223, v207
	v_add_f32_e32 v229, v230, v229
	v_exp_f32_e32 v210, v94
	v_exp_f32_e32 v226, v78
	v_add_f32_e32 v228, v224, v208
	v_add_f32_e32 v229, v228, v229
	v_exp_f32_e32 v211, v95
	v_exp_f32_e32 v227, v79
	v_add_f32_e32 v230, v225, v209
	v_add_f32_e32 v229, v230, v229
	v_add_f32_e32 v228, v226, v210
	v_add_f32_e32 v229, v228, v229
	v_add_f32_e32 v230, v227, v211
	v_add_f32_e32 v95, v230, v229
	v_cvt_pk_bf16_f32 v64, v196, v197
	v_cvt_pk_bf16_f32 v65, v198, v199
	v_cvt_pk_bf16_f32 v66, v200, v201
	v_cvt_pk_bf16_f32 v67, v202, v203
	v_cvt_pk_bf16_f32 v68, v204, v205
	v_cvt_pk_bf16_f32 v69, v206, v207
	v_cvt_pk_bf16_f32 v70, v208, v209
	v_cvt_pk_bf16_f32 v71, v210, v211
	v_cvt_pk_bf16_f32 v72, v212, v213
	v_cvt_pk_bf16_f32 v73, v214, v215
	v_cvt_pk_bf16_f32 v74, v216, v217
	v_cvt_pk_bf16_f32 v75, v218, v219
	v_cvt_pk_bf16_f32 v76, v220, v221
	v_cvt_pk_bf16_f32 v77, v222, v223
	v_cvt_pk_bf16_f32 v78, v224, v225
	v_cvt_pk_bf16_f32 v79, v226, v227
	v_add_f32_e32 v159, v159, v95
	s_waitcnt lgkmcnt(0)
	v_mfma_f32_32x32x16_bf16 v[32:47], v[148:151], v[64:67], v[32:47]
	v_mfma_f32_32x32x16_bf16 v[16:31], v[132:135], v[64:67], v[16:31]
	v_mfma_f32_32x32x16_bf16 v[32:47], v[144:147], v[68:71], v[32:47]
	v_mfma_f32_32x32x16_bf16 v[16:31], v[128:131], v[68:71], v[16:31]
	v_mfma_f32_32x32x16_bf16 v[32:47], v[140:143], v[72:75], v[32:47]
	v_mfma_f32_32x32x16_bf16 v[16:31], v[10:13], v[72:75], v[16:31]
	v_mfma_f32_32x32x16_bf16 v[32:47], v[136:139], v[76:79], v[32:47]
	v_mfma_f32_32x32x16_bf16 v[16:31], v[6:9], v[76:79], v[16:31]
